# rowpass: inner loop fully unrolled, all 8 rows (32 loads) issued before any store; on top of sil + mod split
# baseline (speedup 1.0000x reference)
.LBB0_110:
	s_add_u32 s27, s12, s20
	s_addc_u32 s2, s13, s21
	s_add_i32 s22, s27, 0xffffe000
	s_cmpk_lt_i32 s27, 0x2000
	s_cselect_b32 s3, s2, 0
	s_cselect_b32 s2, s27, s22
	s_cselect_b32 s22, s5, s7
	s_cselect_b32 s23, s4, s6
	s_lshl_b64 s[2:3], s[2:3], 12
	s_add_u32 s2, s23, s2
	s_addc_u32 s3, s22, s3
	global_load_dwordx4 v[44:47], v66, s[2:3]
	global_load_dwordx4 v[40:43], v66, s[2:3] offset:1024
	global_load_dwordx4 v[36:39], v66, s[2:3] offset:2048
	global_load_dwordx4 v[32:35], v66, s[2:3] offset:3072
	s_add_i32 s24, s27, 1
	s_add_i32 s22, s27, 0xffffe001
	s_ashr_i32 s25, s24, 31
	s_cmpk_lt_i32 s24, 0x2000
	s_cselect_b32 s3, s25, 0
	s_cselect_b32 s2, s24, s22
	s_cselect_b32 s23, s5, s7
	s_cselect_b32 s22, s4, s6
	s_lshl_b64 s[2:3], s[2:3], 12
	s_add_u32 s22, s22, s2
	s_addc_u32 s23, s23, s3
	s_add_i32 s28, s27, 2
	s_lshl_b64 s[2:3], s[24:25], 11
	s_add_i32 s24, s27, 0xffffe002
	s_ashr_i32 s29, s28, 31
	v_add_co_u32_e32 v56, vcc, s34, v54
	s_cmpk_lt_i32 s28, 0x2000
	s_nop 0
	v_addc_co_u32_e32 v57, vcc, -1, v55, vcc
	v_lshl_add_u64 v[60:61], v[48:49], 0, s[2:3]
	v_lshl_add_u64 v[58:59], v[50:51], 0, s[2:3]
	s_cselect_b32 s3, s29, 0
	s_cselect_b32 s2, s28, s24
	s_cselect_b32 s25, s5, s7
	s_cselect_b32 s24, s4, s6
	s_lshl_b64 s[2:3], s[2:3], 12
	s_add_u32 s24, s24, s2
	s_addc_u32 s25, s25, s3
	s_add_i32 s26, s27, 3
	s_lshl_b64 s[2:3], s[28:29], 11
	s_add_i32 s28, s27, 0xffffe003
	s_ashr_i32 s27, s26, 31
	s_cmpk_lt_i32 s26, 0x2000
	v_lshl_add_u64 v[64:65], v[48:49], 0, s[2:3]
	v_lshl_add_u64 v[62:63], v[50:51], 0, s[2:3]
	s_cselect_b32 s3, s27, 0
	s_cselect_b32 s2, s26, s28
	s_cselect_b32 s29, s5, s7
	s_cselect_b32 s28, s4, s6
	s_lshl_b64 s[2:3], s[2:3], 12
	s_add_u32 s28, s28, s2
	s_addc_u32 s29, s29, s3
	global_load_dwordx4 v[96:99], v66, s[22:23]
	global_load_dwordx4 v[100:103], v66, s[22:23] offset:1024
	global_load_dwordx4 v[104:107], v66, s[22:23] offset:2048
	global_load_dwordx4 v[108:111], v66, s[22:23] offset:3072
	global_load_dwordx4 v[112:115], v66, s[24:25]
	global_load_dwordx4 v[116:119], v66, s[24:25] offset:1024
	global_load_dwordx4 v[120:123], v66, s[24:25] offset:2048
	global_load_dwordx4 v[124:127], v66, s[24:25] offset:3072
	global_load_dwordx4 v[128:131], v66, s[28:29]
	global_load_dwordx4 v[132:135], v66, s[28:29] offset:1024
	global_load_dwordx4 v[136:139], v66, s[28:29] offset:2048
	global_load_dwordx4 v[140:143], v66, s[28:29] offset:3072
	s_add_u32 s20, s20, 4
	s_addc_u32 s21, s21, 0
	s_add_u32 s27, s12, s20
	s_addc_u32 s2, s13, s21
	s_add_i32 s22, s27, 0xffffe000
	s_cmpk_lt_i32 s27, 0x2000
	s_cselect_b32 s3, s2, 0
	s_cselect_b32 s2, s27, s22
	s_cselect_b32 s22, s5, s7
	s_cselect_b32 s23, s4, s6
	s_lshl_b64 s[2:3], s[2:3], 12
	s_add_u32 s2, s23, s2
	s_addc_u32 s3, s22, s3
	global_load_dwordx4 v[156:159], v66, s[2:3]
	global_load_dwordx4 v[152:155], v66, s[2:3] offset:1024
	global_load_dwordx4 v[148:151], v66, s[2:3] offset:2048
	global_load_dwordx4 v[144:147], v66, s[2:3] offset:3072
	s_add_i32 s24, s27, 1
	s_add_i32 s22, s27, 0xffffe001
	s_ashr_i32 s25, s24, 31
	s_cmpk_lt_i32 s24, 0x2000
	s_cselect_b32 s3, s25, 0
	s_cselect_b32 s2, s24, s22
	s_cselect_b32 s23, s5, s7
	s_cselect_b32 s22, s4, s6
	s_lshl_b64 s[2:3], s[2:3], 12
	s_add_u32 s22, s22, s2
	s_addc_u32 s23, s23, s3
	s_add_i32 s28, s27, 2
	s_lshl_b64 s[2:3], s[24:25], 11
	s_add_i32 s24, s27, 0xffffe002
	s_ashr_i32 s29, s28, 31
	s_cmpk_lt_i32 s28, 0x2000
	s_cselect_b32 s3, s29, 0
	s_cselect_b32 s2, s28, s24
	s_cselect_b32 s25, s5, s7
	s_cselect_b32 s24, s4, s6
	s_lshl_b64 s[2:3], s[2:3], 12
	s_add_u32 s24, s24, s2
	s_addc_u32 s25, s25, s3
	s_add_i32 s26, s27, 3
	s_lshl_b64 s[2:3], s[28:29], 11
	s_add_i32 s28, s27, 0xffffe003
	s_ashr_i32 s27, s26, 31
	s_cmpk_lt_i32 s26, 0x2000
	s_cselect_b32 s3, s27, 0
	s_cselect_b32 s2, s26, s28
	s_cselect_b32 s29, s5, s7
	s_cselect_b32 s28, s4, s6
	s_lshl_b64 s[2:3], s[2:3], 12
	s_add_u32 s28, s28, s2
	s_addc_u32 s29, s29, s3
	global_load_dwordx4 v[160:163], v66, s[22:23]
	global_load_dwordx4 v[164:167], v66, s[22:23] offset:1024
	global_load_dwordx4 v[168:171], v66, s[22:23] offset:2048
	global_load_dwordx4 v[172:175], v66, s[22:23] offset:3072
	global_load_dwordx4 v[176:179], v66, s[24:25]
	global_load_dwordx4 v[180:183], v66, s[24:25] offset:1024
	global_load_dwordx4 v[184:187], v66, s[24:25] offset:2048
	global_load_dwordx4 v[188:191], v66, s[24:25] offset:3072
	global_load_dwordx4 v[192:195], v66, s[28:29]
	global_load_dwordx4 v[196:199], v66, s[28:29] offset:1024
	global_load_dwordx4 v[200:203], v66, s[28:29] offset:2048
	global_load_dwordx4 v[204:207], v66, s[28:29] offset:3072
	s_sub_u32 s20, s20, 4
	s_subb_u32 s21, s21, 0
	s_add_u32 s27, s12, s20
	s_addc_u32 s2, s13, s21
	s_add_i32 s22, s27, 0xffffe000
	s_cmpk_lt_i32 s27, 0x2000
	s_cselect_b32 s3, s2, 0
	s_cselect_b32 s2, s27, s22
	s_cselect_b32 s22, s5, s7
	s_cselect_b32 s23, s4, s6
	s_lshl_b64 s[2:3], s[2:3], 12
	s_add_u32 s2, s23, s2
	s_addc_u32 s3, s22, s3
	s_add_i32 s24, s27, 1
	s_add_i32 s22, s27, 0xffffe001
	s_ashr_i32 s25, s24, 31
	s_cmpk_lt_i32 s24, 0x2000
	s_cselect_b32 s3, s25, 0
	s_cselect_b32 s2, s24, s22
	s_cselect_b32 s23, s5, s7
	s_cselect_b32 s22, s4, s6
	s_lshl_b64 s[2:3], s[2:3], 12
	s_add_u32 s22, s22, s2
	s_addc_u32 s23, s23, s3
	s_add_i32 s28, s27, 2
	s_lshl_b64 s[2:3], s[24:25], 11
	s_add_i32 s24, s27, 0xffffe002
	s_ashr_i32 s29, s28, 31
	s_cmpk_lt_i32 s28, 0x2000
	s_cselect_b32 s3, s29, 0
	s_cselect_b32 s2, s28, s24
	s_cselect_b32 s25, s5, s7
	s_cselect_b32 s24, s4, s6
	s_lshl_b64 s[2:3], s[2:3], 12
	s_add_u32 s24, s24, s2
	s_addc_u32 s25, s25, s3
	s_add_i32 s26, s27, 3
	s_lshl_b64 s[2:3], s[28:29], 11
	s_add_i32 s28, s27, 0xffffe003
	s_ashr_i32 s27, s26, 31
	s_cmpk_lt_i32 s26, 0x2000
	s_cselect_b32 s3, s27, 0
	s_cselect_b32 s2, s26, s28
	s_cselect_b32 s29, s5, s7
	s_cselect_b32 s28, s4, s6
	s_lshl_b64 s[2:3], s[2:3], 12
	s_add_u32 s28, s28, s2
	s_addc_u32 s29, s29, s3
	s_waitcnt vmcnt(31)
	v_cvt_pk_bf16_f32 v72, v44, v45
	v_mul_f32_e32 v74, v45, v45
	v_mul_f32_e32 v75, v47, v47
	s_waitcnt vmcnt(30)
	v_mul_f32_e32 v76, v41, v41
	v_mul_f32_e32 v77, v43, v43
	v_cvt_pk_bf16_f32 v73, v46, v47
	s_waitcnt vmcnt(29)
	v_mul_f32_e32 v78, v37, v37
	v_mul_f32_e32 v79, v39, v39
	global_store_dwordx2 v[54:55], v[72:73], off offset:-1536
	v_cvt_pk_bf16_f32 v72, v40, v41
	v_fmac_f32_e32 v74, v44, v44
	v_fmac_f32_e32 v75, v46, v46
	v_fmac_f32_e32 v76, v40, v40
	v_fmac_f32_e32 v77, v42, v42
	s_waitcnt vmcnt(29)
	v_mul_f32_e32 v80, v33, v33
	v_mul_f32_e32 v81, v35, v35
	v_cvt_pk_bf16_f32 v73, v42, v43
	v_fmac_f32_e32 v78, v36, v36
	v_fmac_f32_e32 v79, v38, v38
	global_store_dwordx2 v[54:55], v[72:73], off offset:-1024
	v_cvt_pk_bf16_f32 v72, v36, v37
	v_add_f32_e32 v74, v74, v75
	v_add_f32_e32 v75, v76, v77
	v_fmac_f32_e32 v80, v32, v32
	v_fmac_f32_e32 v81, v34, v34
	v_cvt_pk_bf16_f32 v73, v38, v39
	v_add_f32_e32 v76, v78, v79
	global_store_dwordx2 v[54:55], v[72:73], off offset:-512
	v_cvt_pk_bf16_f32 v72, v32, v33
	v_add_f32_e32 v74, v74, v75
	v_add_f32_e32 v77, v80, v81
	v_cvt_pk_bf16_f32 v73, v34, v35
	global_store_dwordx2 v[54:55], v[72:73], off
	v_add_f32_e32 v72, v74, v76
	v_add_f32_e32 v72, v72, v77
	v_lshl_add_u64 v[54:55], v[54:55], 0, s[18:19]
	s_nop 0
	v_add_f32_dpp v72, v72, v72 row_ror:8 row_mask:0xf bank_mask:0xf bound_ctrl:1
	s_nop 1
	v_add_f32_dpp v72, v72, v72 row_ror:4 row_mask:0xf bank_mask:0xf bound_ctrl:1
	s_nop 1
	v_add_f32_dpp v72, v72, v72 row_ror:2 row_mask:0xf bank_mask:0xf bound_ctrl:1
	s_nop 1
	v_add_f32_dpp v72, v72, v72 row_ror:1 row_mask:0xf bank_mask:0xf bound_ctrl:1
	v_mov_b32_e32 v73, v72
	s_nop 1
	v_permlane16_swap_b32_e32 v72, v73
	v_add_f32_e32 v72, v72, v73
	v_mov_b32_e32 v73, v72
	s_nop 1
	v_permlane32_swap_b32_e32 v72, v73
	v_add_f32_e32 v72, v72, v73
	v_fmamk_f32 v72, v72, 0x3a800000, v70
	v_mul_f32_e32 v73, 0x4f800000, v72
	v_cmp_gt_f32_e32 vcc, s33, v72
	s_nop 1
	v_cndmask_b32_e32 v72, v72, v73, vcc
	v_sqrt_f32_e32 v73, v72
	s_nop 0
	v_add_u32_e32 v74, -1, v73
	v_add_u32_e32 v75, 1, v73
	v_fma_f32 v76, -v74, v73, v72
	v_fma_f32 v77, -v75, v73, v72
	v_cmp_ge_f32_e64 s[2:3], 0, v76
	s_nop 1
	v_cndmask_b32_e64 v73, v73, v74, s[2:3]
	v_cmp_lt_f32_e64 s[2:3], 0, v77
	s_nop 1
	v_cndmask_b32_e64 v73, v73, v75, s[2:3]
	v_mul_f32_e32 v74, 0x37800000, v73
	v_cndmask_b32_e32 v73, v73, v74, vcc
	v_cmp_class_f32_e32 vcc, v72, v71
	s_nop 1
	v_cndmask_b32_e32 v72, v73, v72, vcc
	v_div_scale_f32 v73, s[2:3], v72, v72, 1.0
	v_rcp_f32_e32 v75, v73
	v_div_scale_f32 v74, vcc, 1.0, v72, 1.0
	v_fma_f32 v76, -v73, v75, 1.0
	v_fmac_f32_e32 v75, v76, v75
	v_mul_f32_e32 v76, v74, v75
	v_fma_f32 v77, -v73, v76, v74
	v_fmac_f32_e32 v76, v77, v75
	v_fma_f32 v73, -v73, v76, v74
	v_div_fmas_f32 v73, v73, v75, v76
	v_div_fixup_f32 v72, v73, v72, 1.0
	v_pk_mul_f32 v[44:45], v[44:45], v[72:73] op_sel_hi:[1,0]
	v_pk_mul_f32 v[40:41], v[40:41], v[72:73] op_sel_hi:[1,0]
	v_pk_mul_f32 v[36:37], v[36:37], v[72:73] op_sel_hi:[1,0]
	v_pk_mul_f32 v[32:33], v[32:33], v[72:73] op_sel_hi:[1,0]
	v_pk_mul_f32 v[46:47], v[46:47], v[72:73] op_sel_hi:[1,0]
	v_pk_mul_f32 v[42:43], v[42:43], v[72:73] op_sel_hi:[1,0]
	v_pk_mul_f32 v[38:39], v[38:39], v[72:73] op_sel_hi:[1,0]
	v_pk_mul_f32 v[34:35], v[34:35], v[72:73] op_sel_hi:[1,0]
	v_pk_fma_f32 v[44:45], v[8:9], v[44:45], v[0:1]
	v_pk_fma_f32 v[40:41], v[12:13], v[40:41], v[4:5]
	v_pk_fma_f32 v[36:37], v[24:25], v[36:37], v[16:17]
	v_pk_fma_f32 v[32:33], v[28:29], v[32:33], v[20:21]
	v_pk_fma_f32 v[46:47], v[10:11], v[46:47], v[2:3]
	v_pk_fma_f32 v[42:43], v[14:15], v[42:43], v[6:7]
	v_pk_fma_f32 v[38:39], v[26:27], v[38:39], v[18:19]
	v_pk_fma_f32 v[34:35], v[30:31], v[34:35], v[22:23]
	v_cvt_pk_bf16_f32 v44, v44, v45
	v_cvt_pk_bf16_f32 v45, v46, v47
	global_store_dwordx2 v[56:57], v[44:45], off offset:-1536
	v_cvt_pk_bf16_f32 v40, v40, v41
	v_cvt_pk_bf16_f32 v41, v42, v43
	global_store_dwordx2 v[56:57], v[40:41], off offset:-1024
	v_cvt_pk_bf16_f32 v36, v36, v37
	v_cvt_pk_bf16_f32 v37, v38, v39
	global_store_dwordx2 v[56:57], v[36:37], off offset:-512
	v_cvt_pk_bf16_f32 v32, v32, v33
	v_cvt_pk_bf16_f32 v33, v34, v35
	global_store_dwordx2 v[56:57], v[32:33], off
	s_waitcnt vmcnt(35)
	v_cvt_pk_bf16_f32 v56, v96, v97
	v_mul_f32_e32 v72, v97, v97
	v_mul_f32_e32 v73, v99, v99
	s_waitcnt vmcnt(34)
	v_mul_f32_e32 v74, v101, v101
	v_mul_f32_e32 v75, v103, v103
	v_cvt_pk_bf16_f32 v57, v98, v99
	s_waitcnt vmcnt(33)
	v_mul_f32_e32 v76, v105, v105
	v_mul_f32_e32 v77, v107, v107
	global_store_dwordx2 v[60:61], v[56:57], off
	v_cvt_pk_bf16_f32 v56, v100, v101
	v_fmac_f32_e32 v72, v96, v96
	v_fmac_f32_e32 v73, v98, v98
	v_fmac_f32_e32 v74, v100, v100
	v_fmac_f32_e32 v75, v102, v102
	s_waitcnt vmcnt(33)
	v_mul_f32_e32 v78, v109, v109
	v_mul_f32_e32 v79, v111, v111
	v_cvt_pk_bf16_f32 v57, v102, v103
	v_fmac_f32_e32 v76, v104, v104
	v_fmac_f32_e32 v77, v106, v106
	global_store_dwordx2 v[60:61], v[56:57], off offset:512
	v_cvt_pk_bf16_f32 v56, v104, v105
	v_add_f32_e32 v72, v72, v73
	v_add_f32_e32 v73, v74, v75
	v_fmac_f32_e32 v78, v108, v108
	v_fmac_f32_e32 v79, v110, v110
	v_cvt_pk_bf16_f32 v57, v106, v107
	v_add_f32_e32 v74, v76, v77
	global_store_dwordx2 v[60:61], v[56:57], off offset:1024
	v_cvt_pk_bf16_f32 v56, v108, v109
	v_add_f32_e32 v72, v72, v73
	v_add_f32_e32 v75, v78, v79
	v_cvt_pk_bf16_f32 v57, v110, v111
	global_store_dwordx2 v[60:61], v[56:57], off offset:1536
	v_add_f32_e32 v56, v72, v74
	v_add_f32_e32 v56, v56, v75
	s_nop 1
	v_add_f32_dpp v56, v56, v56 row_ror:8 row_mask:0xf bank_mask:0xf bound_ctrl:1
	s_nop 1
	v_add_f32_dpp v56, v56, v56 row_ror:4 row_mask:0xf bank_mask:0xf bound_ctrl:1
	s_nop 1
	v_add_f32_dpp v56, v56, v56 row_ror:2 row_mask:0xf bank_mask:0xf bound_ctrl:1
	s_nop 1
	v_add_f32_dpp v56, v56, v56 row_ror:1 row_mask:0xf bank_mask:0xf bound_ctrl:1
	v_mov_b32_e32 v57, v56
	s_nop 1
	v_permlane16_swap_b32_e32 v56, v57
	v_add_f32_e32 v56, v56, v57
	v_mov_b32_e32 v57, v56
	s_nop 1
	v_permlane32_swap_b32_e32 v56, v57
	v_add_f32_e32 v56, v56, v57
	v_fmamk_f32 v56, v56, 0x3a800000, v70
	v_mul_f32_e32 v57, 0x4f800000, v56
	v_cmp_gt_f32_e32 vcc, s33, v56
	s_nop 1
	v_cndmask_b32_e32 v56, v56, v57, vcc
	v_sqrt_f32_e32 v57, v56
	s_nop 0
	v_add_u32_e32 v60, -1, v57
	v_add_u32_e32 v61, 1, v57
	v_fma_f32 v72, -v60, v57, v56
	v_fma_f32 v73, -v61, v57, v56
	v_cmp_ge_f32_e64 s[2:3], 0, v72
	s_nop 1
	v_cndmask_b32_e64 v57, v57, v60, s[2:3]
	v_cmp_lt_f32_e64 s[2:3], 0, v73
	s_nop 1
	v_cndmask_b32_e64 v57, v57, v61, s[2:3]
	v_mul_f32_e32 v60, 0x37800000, v57
	v_cndmask_b32_e32 v57, v57, v60, vcc
	v_cmp_class_f32_e32 vcc, v56, v71
	s_nop 1
	v_cndmask_b32_e32 v56, v57, v56, vcc
	v_div_scale_f32 v57, s[2:3], v56, v56, 1.0
	v_rcp_f32_e32 v61, v57
	v_div_scale_f32 v60, vcc, 1.0, v56, 1.0
	v_fma_f32 v72, -v57, v61, 1.0
	v_fmac_f32_e32 v61, v72, v61
	v_mul_f32_e32 v72, v60, v61
	v_fma_f32 v73, -v57, v72, v60
	v_fmac_f32_e32 v72, v73, v61
	v_fma_f32 v57, -v57, v72, v60
	v_div_fmas_f32 v57, v57, v61, v72
	v_div_fixup_f32 v56, v57, v56, 1.0
	v_pk_mul_f32 v[96:97], v[96:97], v[56:57] op_sel_hi:[1,0]
	v_pk_mul_f32 v[98:99], v[98:99], v[56:57] op_sel_hi:[1,0]
	v_pk_fma_f32 v[96:97], v[8:9], v[96:97], v[0:1]
	v_pk_mul_f32 v[100:101], v[100:101], v[56:57] op_sel_hi:[1,0]
	v_pk_mul_f32 v[102:103], v[102:103], v[56:57] op_sel_hi:[1,0]
	v_pk_fma_f32 v[98:99], v[10:11], v[98:99], v[2:3]
	v_cvt_pk_bf16_f32 v96, v96, v97
	v_pk_mul_f32 v[104:105], v[104:105], v[56:57] op_sel_hi:[1,0]
	v_cvt_pk_bf16_f32 v97, v98, v99
	v_pk_mul_f32 v[106:107], v[106:107], v[56:57] op_sel_hi:[1,0]
	v_pk_fma_f32 v[102:103], v[14:15], v[102:103], v[6:7]
	v_pk_fma_f32 v[100:101], v[12:13], v[100:101], v[4:5]
	global_store_dwordx2 v[58:59], v[96:97], off
	v_cvt_pk_bf16_f32 v96, v100, v101
	v_cvt_pk_bf16_f32 v97, v102, v103
	v_pk_mul_f32 v[108:109], v[108:109], v[56:57] op_sel_hi:[1,0]
	v_pk_mul_f32 v[110:111], v[110:111], v[56:57] op_sel_hi:[1,0]
	v_pk_fma_f32 v[106:107], v[26:27], v[106:107], v[18:19]
	v_pk_fma_f32 v[104:105], v[24:25], v[104:105], v[16:17]
	global_store_dwordx2 v[58:59], v[96:97], off offset:512
	v_cvt_pk_bf16_f32 v96, v104, v105
	v_cvt_pk_bf16_f32 v97, v106, v107
	v_pk_fma_f32 v[110:111], v[30:31], v[110:111], v[22:23]
	v_pk_fma_f32 v[108:109], v[28:29], v[108:109], v[20:21]
	global_store_dwordx2 v[58:59], v[96:97], off offset:1024
	v_cvt_pk_bf16_f32 v96, v108, v109
	v_cvt_pk_bf16_f32 v97, v110, v111
	global_store_dwordx2 v[58:59], v[96:97], off offset:1536
	s_waitcnt vmcnt(39)
	v_cvt_pk_bf16_f32 v56, v112, v113
	v_mul_f32_e32 v58, v113, v113
	v_mul_f32_e32 v59, v115, v115
	s_waitcnt vmcnt(38)
	v_mul_f32_e32 v60, v117, v117
	v_mul_f32_e32 v61, v119, v119
	v_cvt_pk_bf16_f32 v57, v114, v115
	s_waitcnt vmcnt(37)
	v_mul_f32_e32 v72, v121, v121
	v_mul_f32_e32 v73, v123, v123
	global_store_dwordx2 v[64:65], v[56:57], off
	v_cvt_pk_bf16_f32 v56, v116, v117
	v_fmac_f32_e32 v58, v112, v112
	v_fmac_f32_e32 v59, v114, v114
	v_fmac_f32_e32 v60, v116, v116
	v_fmac_f32_e32 v61, v118, v118
	s_waitcnt vmcnt(37)
	v_mul_f32_e32 v74, v125, v125
	v_mul_f32_e32 v75, v127, v127
	v_cvt_pk_bf16_f32 v57, v118, v119
	v_fmac_f32_e32 v72, v120, v120
	v_fmac_f32_e32 v73, v122, v122
	global_store_dwordx2 v[64:65], v[56:57], off offset:512
	v_cvt_pk_bf16_f32 v56, v120, v121
	v_add_f32_e32 v58, v58, v59
	v_add_f32_e32 v59, v60, v61
	v_fmac_f32_e32 v74, v124, v124
	v_fmac_f32_e32 v75, v126, v126
	v_cvt_pk_bf16_f32 v57, v122, v123
	v_add_f32_e32 v60, v72, v73
	global_store_dwordx2 v[64:65], v[56:57], off offset:1024
	v_cvt_pk_bf16_f32 v56, v124, v125
	v_add_f32_e32 v58, v58, v59
	v_add_f32_e32 v61, v74, v75
	v_cvt_pk_bf16_f32 v57, v126, v127
	global_store_dwordx2 v[64:65], v[56:57], off offset:1536
	v_add_f32_e32 v56, v58, v60
	v_add_f32_e32 v56, v56, v61
	s_nop 1
	v_add_f32_dpp v56, v56, v56 row_ror:8 row_mask:0xf bank_mask:0xf bound_ctrl:1
	s_nop 1
	v_add_f32_dpp v56, v56, v56 row_ror:4 row_mask:0xf bank_mask:0xf bound_ctrl:1
	s_nop 1
	v_add_f32_dpp v56, v56, v56 row_ror:2 row_mask:0xf bank_mask:0xf bound_ctrl:1
	s_nop 1
	v_add_f32_dpp v56, v56, v56 row_ror:1 row_mask:0xf bank_mask:0xf bound_ctrl:1
	v_mov_b32_e32 v57, v56
	s_nop 1
	v_permlane16_swap_b32_e32 v56, v57
	v_add_f32_e32 v56, v56, v57
	v_mov_b32_e32 v57, v56
	s_nop 1
	v_permlane32_swap_b32_e32 v56, v57
	v_add_f32_e32 v56, v56, v57
	v_fmamk_f32 v56, v56, 0x3a800000, v70
	v_mul_f32_e32 v57, 0x4f800000, v56
	v_cmp_gt_f32_e32 vcc, s33, v56
	s_nop 1
	v_cndmask_b32_e32 v56, v56, v57, vcc
	v_sqrt_f32_e32 v57, v56
	s_nop 0
	v_add_u32_e32 v58, -1, v57
	v_add_u32_e32 v59, 1, v57
	v_fma_f32 v60, -v58, v57, v56
	v_fma_f32 v61, -v59, v57, v56
	v_cmp_ge_f32_e64 s[2:3], 0, v60
	s_nop 1
	v_cndmask_b32_e64 v57, v57, v58, s[2:3]
	v_cmp_lt_f32_e64 s[2:3], 0, v61
	s_nop 1
	v_cndmask_b32_e64 v57, v57, v59, s[2:3]
	v_mul_f32_e32 v58, 0x37800000, v57
	v_cndmask_b32_e32 v57, v57, v58, vcc
	v_cmp_class_f32_e32 vcc, v56, v71
	s_nop 1
	v_cndmask_b32_e32 v56, v57, v56, vcc
	v_div_scale_f32 v57, s[2:3], v56, v56, 1.0
	v_rcp_f32_e32 v59, v57
	v_div_scale_f32 v58, vcc, 1.0, v56, 1.0
	s_lshl_b64 s[2:3], s[26:27], 11
	v_fma_f32 v60, -v57, v59, 1.0
	v_fmac_f32_e32 v59, v60, v59
	v_mul_f32_e32 v60, v58, v59
	v_fma_f32 v61, -v57, v60, v58
	v_fmac_f32_e32 v60, v61, v59
	v_fma_f32 v57, -v57, v60, v58
	v_div_fmas_f32 v57, v57, v59, v60
	v_div_fixup_f32 v56, v57, v56, 1.0
	v_pk_mul_f32 v[112:113], v[112:113], v[56:57] op_sel_hi:[1,0]
	v_pk_mul_f32 v[114:115], v[114:115], v[56:57] op_sel_hi:[1,0]
	v_pk_fma_f32 v[112:113], v[8:9], v[112:113], v[0:1]
	v_pk_mul_f32 v[116:117], v[116:117], v[56:57] op_sel_hi:[1,0]
	v_pk_mul_f32 v[118:119], v[118:119], v[56:57] op_sel_hi:[1,0]
	v_pk_fma_f32 v[114:115], v[10:11], v[114:115], v[2:3]
	v_cvt_pk_bf16_f32 v112, v112, v113
	v_pk_mul_f32 v[120:121], v[120:121], v[56:57] op_sel_hi:[1,0]
	v_cvt_pk_bf16_f32 v113, v114, v115
	v_pk_mul_f32 v[122:123], v[122:123], v[56:57] op_sel_hi:[1,0]
	v_pk_fma_f32 v[118:119], v[14:15], v[118:119], v[6:7]
	v_pk_fma_f32 v[116:117], v[12:13], v[116:117], v[4:5]
	global_store_dwordx2 v[62:63], v[112:113], off
	v_cvt_pk_bf16_f32 v112, v116, v117
	v_cvt_pk_bf16_f32 v113, v118, v119
	v_pk_mul_f32 v[124:125], v[124:125], v[56:57] op_sel_hi:[1,0]
	v_pk_mul_f32 v[126:127], v[126:127], v[56:57] op_sel_hi:[1,0]
	v_pk_fma_f32 v[122:123], v[26:27], v[122:123], v[18:19]
	v_pk_fma_f32 v[120:121], v[24:25], v[120:121], v[16:17]
	global_store_dwordx2 v[62:63], v[112:113], off offset:512
	v_cvt_pk_bf16_f32 v112, v120, v121
	v_cvt_pk_bf16_f32 v113, v122, v123
	v_pk_fma_f32 v[126:127], v[30:31], v[126:127], v[22:23]
	v_pk_fma_f32 v[124:125], v[28:29], v[124:125], v[20:21]
	global_store_dwordx2 v[62:63], v[112:113], off offset:1024
	v_cvt_pk_bf16_f32 v112, v124, v125
	v_cvt_pk_bf16_f32 v113, v126, v127
	global_store_dwordx2 v[62:63], v[112:113], off offset:1536
	v_lshl_add_u64 v[56:57], v[48:49], 0, s[2:3]
	s_waitcnt vmcnt(43)
	v_cvt_pk_bf16_f32 v60, v128, v129
	v_mul_f32_e32 v62, v129, v129
	v_mul_f32_e32 v63, v131, v131
	s_waitcnt vmcnt(42)
	v_mul_f32_e32 v64, v133, v133
	v_mul_f32_e32 v65, v135, v135
	v_cvt_pk_bf16_f32 v61, v130, v131
	s_waitcnt vmcnt(41)
	v_mul_f32_e32 v72, v137, v137
	v_mul_f32_e32 v73, v139, v139
	v_fmac_f32_e32 v62, v128, v128
	v_fmac_f32_e32 v63, v130, v130
	v_fmac_f32_e32 v64, v132, v132
	v_fmac_f32_e32 v65, v134, v134
	s_waitcnt vmcnt(40)
	v_mul_f32_e32 v74, v141, v141
	v_mul_f32_e32 v75, v143, v143
	global_store_dwordx2 v[56:57], v[60:61], off
	v_cvt_pk_bf16_f32 v60, v132, v133
	v_cvt_pk_bf16_f32 v61, v134, v135
	v_fmac_f32_e32 v72, v136, v136
	v_fmac_f32_e32 v73, v138, v138
	v_add_f32_e32 v62, v62, v63
	v_add_f32_e32 v63, v64, v65
	v_fmac_f32_e32 v74, v140, v140
	v_fmac_f32_e32 v75, v142, v142
	global_store_dwordx2 v[56:57], v[60:61], off offset:512
	v_cvt_pk_bf16_f32 v60, v136, v137
	v_cvt_pk_bf16_f32 v61, v138, v139
	v_add_f32_e32 v64, v72, v73
	v_add_f32_e32 v62, v62, v63
	v_add_f32_e32 v65, v74, v75
	global_store_dwordx2 v[56:57], v[60:61], off offset:1024
	v_cvt_pk_bf16_f32 v60, v140, v141
	v_cvt_pk_bf16_f32 v61, v142, v143
	global_store_dwordx2 v[56:57], v[60:61], off offset:1536
	v_add_f32_e32 v56, v62, v64
	v_add_f32_e32 v56, v56, v65
	v_lshl_add_u64 v[58:59], v[50:51], 0, s[2:3]
	s_add_u32 s20, s20, 4
	v_add_f32_dpp v56, v56, v56 row_ror:8 row_mask:0xf bank_mask:0xf bound_ctrl:1
	s_addc_u32 s21, s21, 0
	s_cmp_eq_u32 s20, 8
	v_add_f32_dpp v56, v56, v56 row_ror:4 row_mask:0xf bank_mask:0xf bound_ctrl:1
	s_nop 1
	v_add_f32_dpp v56, v56, v56 row_ror:2 row_mask:0xf bank_mask:0xf bound_ctrl:1
	s_nop 1
	v_add_f32_dpp v56, v56, v56 row_ror:1 row_mask:0xf bank_mask:0xf bound_ctrl:1
	v_mov_b32_e32 v57, v56
	s_nop 1
	v_permlane16_swap_b32_e32 v56, v57
	v_add_f32_e32 v56, v56, v57
	v_mov_b32_e32 v57, v56
	s_nop 1
	v_permlane32_swap_b32_e32 v56, v57
	v_add_f32_e32 v56, v56, v57
	v_fmamk_f32 v56, v56, 0x3a800000, v70
	v_mul_f32_e32 v57, 0x4f800000, v56
	v_cmp_gt_f32_e32 vcc, s33, v56
	s_nop 1
	v_cndmask_b32_e32 v56, v56, v57, vcc
	v_sqrt_f32_e32 v57, v56
	s_nop 0
	v_add_u32_e32 v60, -1, v57
	v_add_u32_e32 v61, 1, v57
	v_fma_f32 v62, -v60, v57, v56
	v_fma_f32 v63, -v61, v57, v56
	v_cmp_ge_f32_e64 s[2:3], 0, v62
	s_nop 1
	v_cndmask_b32_e64 v57, v57, v60, s[2:3]
	v_cmp_lt_f32_e64 s[2:3], 0, v63
	s_nop 1
	v_cndmask_b32_e64 v57, v57, v61, s[2:3]
	v_mul_f32_e32 v60, 0x37800000, v57
	v_cndmask_b32_e32 v57, v57, v60, vcc
	v_cmp_class_f32_e32 vcc, v56, v71
	s_nop 1
	v_cndmask_b32_e32 v56, v57, v56, vcc
	v_div_scale_f32 v57, s[2:3], v56, v56, 1.0
	v_rcp_f32_e32 v61, v57
	v_div_scale_f32 v60, vcc, 1.0, v56, 1.0
	v_fma_f32 v62, -v57, v61, 1.0
	v_fmac_f32_e32 v61, v62, v61
	v_mul_f32_e32 v62, v60, v61
	v_fma_f32 v63, -v57, v62, v60
	v_fmac_f32_e32 v62, v63, v61
	v_fma_f32 v57, -v57, v62, v60
	v_div_fmas_f32 v57, v57, v61, v62
	v_div_fixup_f32 v56, v57, v56, 1.0
	v_pk_mul_f32 v[128:129], v[128:129], v[56:57] op_sel_hi:[1,0]
	v_pk_mul_f32 v[130:131], v[130:131], v[56:57] op_sel_hi:[1,0]
	v_pk_fma_f32 v[128:129], v[8:9], v[128:129], v[0:1]
	v_pk_mul_f32 v[132:133], v[132:133], v[56:57] op_sel_hi:[1,0]
	v_pk_mul_f32 v[134:135], v[134:135], v[56:57] op_sel_hi:[1,0]
	v_pk_fma_f32 v[130:131], v[10:11], v[130:131], v[2:3]
	v_cvt_pk_bf16_f32 v128, v128, v129
	v_pk_mul_f32 v[136:137], v[136:137], v[56:57] op_sel_hi:[1,0]
	v_cvt_pk_bf16_f32 v129, v130, v131
	v_pk_mul_f32 v[138:139], v[138:139], v[56:57] op_sel_hi:[1,0]
	v_pk_fma_f32 v[134:135], v[14:15], v[134:135], v[6:7]
	v_pk_fma_f32 v[132:133], v[12:13], v[132:133], v[4:5]
	global_store_dwordx2 v[58:59], v[128:129], off
	v_cvt_pk_bf16_f32 v128, v132, v133
	v_cvt_pk_bf16_f32 v129, v134, v135
	v_pk_mul_f32 v[140:141], v[140:141], v[56:57] op_sel_hi:[1,0]
	v_pk_mul_f32 v[142:143], v[142:143], v[56:57] op_sel_hi:[1,0]
	v_pk_fma_f32 v[138:139], v[26:27], v[138:139], v[18:19]
	v_pk_fma_f32 v[136:137], v[24:25], v[136:137], v[16:17]
	global_store_dwordx2 v[58:59], v[128:129], off offset:512
	v_cvt_pk_bf16_f32 v128, v136, v137
	v_cvt_pk_bf16_f32 v129, v138, v139
	v_pk_fma_f32 v[142:143], v[30:31], v[142:143], v[22:23]
	v_pk_fma_f32 v[140:141], v[28:29], v[140:141], v[20:21]
	global_store_dwordx2 v[58:59], v[128:129], off offset:1024
	v_cvt_pk_bf16_f32 v128, v140, v141
	v_cvt_pk_bf16_f32 v129, v142, v143
	global_store_dwordx2 v[58:59], v[128:129], off offset:1536
	s_add_u32 s27, s12, s20
	s_addc_u32 s2, s13, s21
	s_add_i32 s22, s27, 0xffffe000
	s_cmpk_lt_i32 s27, 0x2000
	s_cselect_b32 s3, s2, 0
	s_cselect_b32 s2, s27, s22
	s_cselect_b32 s22, s5, s7
	s_cselect_b32 s23, s4, s6
	s_lshl_b64 s[2:3], s[2:3], 12
	s_add_u32 s2, s23, s2
	s_addc_u32 s3, s22, s3
	s_add_i32 s24, s27, 1
	s_add_i32 s22, s27, 0xffffe001
	s_ashr_i32 s25, s24, 31
	s_cmpk_lt_i32 s24, 0x2000
	s_cselect_b32 s3, s25, 0
	s_cselect_b32 s2, s24, s22
	s_cselect_b32 s23, s5, s7
	s_cselect_b32 s22, s4, s6
	s_lshl_b64 s[2:3], s[2:3], 12
	s_add_u32 s22, s22, s2
	s_addc_u32 s23, s23, s3
	s_add_i32 s28, s27, 2
	s_lshl_b64 s[2:3], s[24:25], 11
	s_add_i32 s24, s27, 0xffffe002
	s_ashr_i32 s29, s28, 31
	v_add_co_u32_e32 v56, vcc, s34, v54
	s_cmpk_lt_i32 s28, 0x2000
	s_nop 0
	v_addc_co_u32_e32 v57, vcc, -1, v55, vcc
	v_lshl_add_u64 v[60:61], v[48:49], 0, s[2:3]
	v_lshl_add_u64 v[58:59], v[50:51], 0, s[2:3]
	s_cselect_b32 s3, s29, 0
	s_cselect_b32 s2, s28, s24
	s_cselect_b32 s25, s5, s7
	s_cselect_b32 s24, s4, s6
	s_lshl_b64 s[2:3], s[2:3], 12
	s_add_u32 s24, s24, s2
	s_addc_u32 s25, s25, s3
	s_add_i32 s26, s27, 3
	s_lshl_b64 s[2:3], s[28:29], 11
	s_add_i32 s28, s27, 0xffffe003
	s_ashr_i32 s27, s26, 31
	s_cmpk_lt_i32 s26, 0x2000
	v_lshl_add_u64 v[64:65], v[48:49], 0, s[2:3]
	v_lshl_add_u64 v[62:63], v[50:51], 0, s[2:3]
	s_cselect_b32 s3, s27, 0
	s_cselect_b32 s2, s26, s28
	s_cselect_b32 s29, s5, s7
	s_cselect_b32 s28, s4, s6
	s_lshl_b64 s[2:3], s[2:3], 12
	s_add_u32 s28, s28, s2
	s_addc_u32 s29, s29, s3
	s_waitcnt vmcnt(47)
	v_cvt_pk_bf16_f32 v72, v156, v157
	v_mul_f32_e32 v74, v157, v157
	v_mul_f32_e32 v75, v159, v159
	s_waitcnt vmcnt(46)
	v_mul_f32_e32 v76, v153, v153
	v_mul_f32_e32 v77, v155, v155
	v_cvt_pk_bf16_f32 v73, v158, v159
	s_waitcnt vmcnt(45)
	v_mul_f32_e32 v78, v149, v149
	v_mul_f32_e32 v79, v151, v151
	global_store_dwordx2 v[54:55], v[72:73], off offset:-1536
	v_cvt_pk_bf16_f32 v72, v152, v153
	v_fmac_f32_e32 v74, v156, v156
	v_fmac_f32_e32 v75, v158, v158
	v_fmac_f32_e32 v76, v152, v152
	v_fmac_f32_e32 v77, v154, v154
	s_waitcnt vmcnt(45)
	v_mul_f32_e32 v80, v145, v145
	v_mul_f32_e32 v81, v147, v147
	v_cvt_pk_bf16_f32 v73, v154, v155
	v_fmac_f32_e32 v78, v148, v148
	v_fmac_f32_e32 v79, v150, v150
	global_store_dwordx2 v[54:55], v[72:73], off offset:-1024
	v_cvt_pk_bf16_f32 v72, v148, v149
	v_add_f32_e32 v74, v74, v75
	v_add_f32_e32 v75, v76, v77
	v_fmac_f32_e32 v80, v144, v144
	v_fmac_f32_e32 v81, v146, v146
	v_cvt_pk_bf16_f32 v73, v150, v151
	v_add_f32_e32 v76, v78, v79
	global_store_dwordx2 v[54:55], v[72:73], off offset:-512
	v_cvt_pk_bf16_f32 v72, v144, v145
	v_add_f32_e32 v74, v74, v75
	v_add_f32_e32 v77, v80, v81
	v_cvt_pk_bf16_f32 v73, v146, v147
	global_store_dwordx2 v[54:55], v[72:73], off
	v_add_f32_e32 v72, v74, v76
	v_add_f32_e32 v72, v72, v77
	v_lshl_add_u64 v[54:55], v[54:55], 0, s[18:19]
	s_nop 0
	v_add_f32_dpp v72, v72, v72 row_ror:8 row_mask:0xf bank_mask:0xf bound_ctrl:1
	s_nop 1
	v_add_f32_dpp v72, v72, v72 row_ror:4 row_mask:0xf bank_mask:0xf bound_ctrl:1
	s_nop 1
	v_add_f32_dpp v72, v72, v72 row_ror:2 row_mask:0xf bank_mask:0xf bound_ctrl:1
	s_nop 1
	v_add_f32_dpp v72, v72, v72 row_ror:1 row_mask:0xf bank_mask:0xf bound_ctrl:1
	v_mov_b32_e32 v73, v72
	s_nop 1
	v_permlane16_swap_b32_e32 v72, v73
	v_add_f32_e32 v72, v72, v73
	v_mov_b32_e32 v73, v72
	s_nop 1
	v_permlane32_swap_b32_e32 v72, v73
	v_add_f32_e32 v72, v72, v73
	v_fmamk_f32 v72, v72, 0x3a800000, v70
	v_mul_f32_e32 v73, 0x4f800000, v72
	v_cmp_gt_f32_e32 vcc, s33, v72
	s_nop 1
	v_cndmask_b32_e32 v72, v72, v73, vcc
	v_sqrt_f32_e32 v73, v72
	s_nop 0
	v_add_u32_e32 v74, -1, v73
	v_add_u32_e32 v75, 1, v73
	v_fma_f32 v76, -v74, v73, v72
	v_fma_f32 v77, -v75, v73, v72
	v_cmp_ge_f32_e64 s[2:3], 0, v76
	s_nop 1
	v_cndmask_b32_e64 v73, v73, v74, s[2:3]
	v_cmp_lt_f32_e64 s[2:3], 0, v77
	s_nop 1
	v_cndmask_b32_e64 v73, v73, v75, s[2:3]
	v_mul_f32_e32 v74, 0x37800000, v73
	v_cndmask_b32_e32 v73, v73, v74, vcc
	v_cmp_class_f32_e32 vcc, v72, v71
	s_nop 1
	v_cndmask_b32_e32 v72, v73, v72, vcc
	v_div_scale_f32 v73, s[2:3], v72, v72, 1.0
	v_rcp_f32_e32 v75, v73
	v_div_scale_f32 v74, vcc, 1.0, v72, 1.0
	v_fma_f32 v76, -v73, v75, 1.0
	v_fmac_f32_e32 v75, v76, v75
	v_mul_f32_e32 v76, v74, v75
	v_fma_f32 v77, -v73, v76, v74
	v_fmac_f32_e32 v76, v77, v75
	v_fma_f32 v73, -v73, v76, v74
	v_div_fmas_f32 v73, v73, v75, v76
	v_div_fixup_f32 v72, v73, v72, 1.0
	v_pk_mul_f32 v[156:157], v[156:157], v[72:73] op_sel_hi:[1,0]
	v_pk_mul_f32 v[152:153], v[152:153], v[72:73] op_sel_hi:[1,0]
	v_pk_mul_f32 v[148:149], v[148:149], v[72:73] op_sel_hi:[1,0]
	v_pk_mul_f32 v[144:145], v[144:145], v[72:73] op_sel_hi:[1,0]
	v_pk_mul_f32 v[158:159], v[158:159], v[72:73] op_sel_hi:[1,0]
	v_pk_mul_f32 v[154:155], v[154:155], v[72:73] op_sel_hi:[1,0]
	v_pk_mul_f32 v[150:151], v[150:151], v[72:73] op_sel_hi:[1,0]
	v_pk_mul_f32 v[146:147], v[146:147], v[72:73] op_sel_hi:[1,0]
	v_pk_fma_f32 v[156:157], v[8:9], v[156:157], v[0:1]
	v_pk_fma_f32 v[152:153], v[12:13], v[152:153], v[4:5]
	v_pk_fma_f32 v[148:149], v[24:25], v[148:149], v[16:17]
	v_pk_fma_f32 v[144:145], v[28:29], v[144:145], v[20:21]
	v_pk_fma_f32 v[158:159], v[10:11], v[158:159], v[2:3]
	v_pk_fma_f32 v[154:155], v[14:15], v[154:155], v[6:7]
	v_pk_fma_f32 v[150:151], v[26:27], v[150:151], v[18:19]
	v_pk_fma_f32 v[146:147], v[30:31], v[146:147], v[22:23]
	v_cvt_pk_bf16_f32 v156, v156, v157
	v_cvt_pk_bf16_f32 v157, v158, v159
	global_store_dwordx2 v[56:57], v[156:157], off offset:-1536
	v_cvt_pk_bf16_f32 v152, v152, v153
	v_cvt_pk_bf16_f32 v153, v154, v155
	global_store_dwordx2 v[56:57], v[152:153], off offset:-1024
	v_cvt_pk_bf16_f32 v148, v148, v149
	v_cvt_pk_bf16_f32 v149, v150, v151
	global_store_dwordx2 v[56:57], v[148:149], off offset:-512
	v_cvt_pk_bf16_f32 v144, v144, v145
	v_cvt_pk_bf16_f32 v145, v146, v147
	global_store_dwordx2 v[56:57], v[144:145], off
	s_waitcnt vmcnt(51)
	v_cvt_pk_bf16_f32 v56, v160, v161
	v_mul_f32_e32 v72, v161, v161
	v_mul_f32_e32 v73, v163, v163
	s_waitcnt vmcnt(50)
	v_mul_f32_e32 v74, v165, v165
	v_mul_f32_e32 v75, v167, v167
	v_cvt_pk_bf16_f32 v57, v162, v163
	s_waitcnt vmcnt(49)
	v_mul_f32_e32 v76, v169, v169
	v_mul_f32_e32 v77, v171, v171
	global_store_dwordx2 v[60:61], v[56:57], off
	v_cvt_pk_bf16_f32 v56, v164, v165
	v_fmac_f32_e32 v72, v160, v160
	v_fmac_f32_e32 v73, v162, v162
	v_fmac_f32_e32 v74, v164, v164
	v_fmac_f32_e32 v75, v166, v166
	s_waitcnt vmcnt(49)
	v_mul_f32_e32 v78, v173, v173
	v_mul_f32_e32 v79, v175, v175
	v_cvt_pk_bf16_f32 v57, v166, v167
	v_fmac_f32_e32 v76, v168, v168
	v_fmac_f32_e32 v77, v170, v170
	global_store_dwordx2 v[60:61], v[56:57], off offset:512
	v_cvt_pk_bf16_f32 v56, v168, v169
	v_add_f32_e32 v72, v72, v73
	v_add_f32_e32 v73, v74, v75
	v_fmac_f32_e32 v78, v172, v172
	v_fmac_f32_e32 v79, v174, v174
	v_cvt_pk_bf16_f32 v57, v170, v171
	v_add_f32_e32 v74, v76, v77
	global_store_dwordx2 v[60:61], v[56:57], off offset:1024
	v_cvt_pk_bf16_f32 v56, v172, v173
	v_add_f32_e32 v72, v72, v73
	v_add_f32_e32 v75, v78, v79
	v_cvt_pk_bf16_f32 v57, v174, v175
	global_store_dwordx2 v[60:61], v[56:57], off offset:1536
	v_add_f32_e32 v56, v72, v74
	v_add_f32_e32 v56, v56, v75
	s_nop 1
	v_add_f32_dpp v56, v56, v56 row_ror:8 row_mask:0xf bank_mask:0xf bound_ctrl:1
	s_nop 1
	v_add_f32_dpp v56, v56, v56 row_ror:4 row_mask:0xf bank_mask:0xf bound_ctrl:1
	s_nop 1
	v_add_f32_dpp v56, v56, v56 row_ror:2 row_mask:0xf bank_mask:0xf bound_ctrl:1
	s_nop 1
	v_add_f32_dpp v56, v56, v56 row_ror:1 row_mask:0xf bank_mask:0xf bound_ctrl:1
	v_mov_b32_e32 v57, v56
	s_nop 1
	v_permlane16_swap_b32_e32 v56, v57
	v_add_f32_e32 v56, v56, v57
	v_mov_b32_e32 v57, v56
	s_nop 1
	v_permlane32_swap_b32_e32 v56, v57
	v_add_f32_e32 v56, v56, v57
	v_fmamk_f32 v56, v56, 0x3a800000, v70
	v_mul_f32_e32 v57, 0x4f800000, v56
	v_cmp_gt_f32_e32 vcc, s33, v56
	s_nop 1
	v_cndmask_b32_e32 v56, v56, v57, vcc
	v_sqrt_f32_e32 v57, v56
	s_nop 0
	v_add_u32_e32 v60, -1, v57
	v_add_u32_e32 v61, 1, v57
	v_fma_f32 v72, -v60, v57, v56
	v_fma_f32 v73, -v61, v57, v56
	v_cmp_ge_f32_e64 s[2:3], 0, v72
	s_nop 1
	v_cndmask_b32_e64 v57, v57, v60, s[2:3]
	v_cmp_lt_f32_e64 s[2:3], 0, v73
	s_nop 1
	v_cndmask_b32_e64 v57, v57, v61, s[2:3]
	v_mul_f32_e32 v60, 0x37800000, v57
	v_cndmask_b32_e32 v57, v57, v60, vcc
	v_cmp_class_f32_e32 vcc, v56, v71
	s_nop 1
	v_cndmask_b32_e32 v56, v57, v56, vcc
	v_div_scale_f32 v57, s[2:3], v56, v56, 1.0
	v_rcp_f32_e32 v61, v57
	v_div_scale_f32 v60, vcc, 1.0, v56, 1.0
	v_fma_f32 v72, -v57, v61, 1.0
	v_fmac_f32_e32 v61, v72, v61
	v_mul_f32_e32 v72, v60, v61
	v_fma_f32 v73, -v57, v72, v60
	v_fmac_f32_e32 v72, v73, v61
	v_fma_f32 v57, -v57, v72, v60
	v_div_fmas_f32 v57, v57, v61, v72
	v_div_fixup_f32 v56, v57, v56, 1.0
	v_pk_mul_f32 v[160:161], v[160:161], v[56:57] op_sel_hi:[1,0]
	v_pk_mul_f32 v[162:163], v[162:163], v[56:57] op_sel_hi:[1,0]
	v_pk_fma_f32 v[160:161], v[8:9], v[160:161], v[0:1]
	v_pk_mul_f32 v[164:165], v[164:165], v[56:57] op_sel_hi:[1,0]
	v_pk_mul_f32 v[166:167], v[166:167], v[56:57] op_sel_hi:[1,0]
	v_pk_fma_f32 v[162:163], v[10:11], v[162:163], v[2:3]
	v_cvt_pk_bf16_f32 v160, v160, v161
	v_pk_mul_f32 v[168:169], v[168:169], v[56:57] op_sel_hi:[1,0]
	v_cvt_pk_bf16_f32 v161, v162, v163
	v_pk_mul_f32 v[170:171], v[170:171], v[56:57] op_sel_hi:[1,0]
	v_pk_fma_f32 v[166:167], v[14:15], v[166:167], v[6:7]
	v_pk_fma_f32 v[164:165], v[12:13], v[164:165], v[4:5]
	global_store_dwordx2 v[58:59], v[160:161], off
	v_cvt_pk_bf16_f32 v160, v164, v165
	v_cvt_pk_bf16_f32 v161, v166, v167
	v_pk_mul_f32 v[172:173], v[172:173], v[56:57] op_sel_hi:[1,0]
	v_pk_mul_f32 v[174:175], v[174:175], v[56:57] op_sel_hi:[1,0]
	v_pk_fma_f32 v[170:171], v[26:27], v[170:171], v[18:19]
	v_pk_fma_f32 v[168:169], v[24:25], v[168:169], v[16:17]
	global_store_dwordx2 v[58:59], v[160:161], off offset:512
	v_cvt_pk_bf16_f32 v160, v168, v169
	v_cvt_pk_bf16_f32 v161, v170, v171
	v_pk_fma_f32 v[174:175], v[30:31], v[174:175], v[22:23]
	v_pk_fma_f32 v[172:173], v[28:29], v[172:173], v[20:21]
	global_store_dwordx2 v[58:59], v[160:161], off offset:1024
	v_cvt_pk_bf16_f32 v160, v172, v173
	v_cvt_pk_bf16_f32 v161, v174, v175
	global_store_dwordx2 v[58:59], v[160:161], off offset:1536
	s_waitcnt vmcnt(55)
	v_cvt_pk_bf16_f32 v56, v176, v177
	v_mul_f32_e32 v58, v177, v177
	v_mul_f32_e32 v59, v179, v179
	s_waitcnt vmcnt(54)
	v_mul_f32_e32 v60, v181, v181
	v_mul_f32_e32 v61, v183, v183
	v_cvt_pk_bf16_f32 v57, v178, v179
	s_waitcnt vmcnt(53)
	v_mul_f32_e32 v72, v185, v185
	v_mul_f32_e32 v73, v187, v187
	global_store_dwordx2 v[64:65], v[56:57], off
	v_cvt_pk_bf16_f32 v56, v180, v181
	v_fmac_f32_e32 v58, v176, v176
	v_fmac_f32_e32 v59, v178, v178
	v_fmac_f32_e32 v60, v180, v180
	v_fmac_f32_e32 v61, v182, v182
	s_waitcnt vmcnt(53)
	v_mul_f32_e32 v74, v189, v189
	v_mul_f32_e32 v75, v191, v191
	v_cvt_pk_bf16_f32 v57, v182, v183
	v_fmac_f32_e32 v72, v184, v184
	v_fmac_f32_e32 v73, v186, v186
	global_store_dwordx2 v[64:65], v[56:57], off offset:512
	v_cvt_pk_bf16_f32 v56, v184, v185
	v_add_f32_e32 v58, v58, v59
	v_add_f32_e32 v59, v60, v61
	v_fmac_f32_e32 v74, v188, v188
	v_fmac_f32_e32 v75, v190, v190
	v_cvt_pk_bf16_f32 v57, v186, v187
	v_add_f32_e32 v60, v72, v73
	global_store_dwordx2 v[64:65], v[56:57], off offset:1024
	v_cvt_pk_bf16_f32 v56, v188, v189
	v_add_f32_e32 v58, v58, v59
	v_add_f32_e32 v61, v74, v75
	v_cvt_pk_bf16_f32 v57, v190, v191
	global_store_dwordx2 v[64:65], v[56:57], off offset:1536
	v_add_f32_e32 v56, v58, v60
	v_add_f32_e32 v56, v56, v61
	s_nop 1
	v_add_f32_dpp v56, v56, v56 row_ror:8 row_mask:0xf bank_mask:0xf bound_ctrl:1
	s_nop 1
	v_add_f32_dpp v56, v56, v56 row_ror:4 row_mask:0xf bank_mask:0xf bound_ctrl:1
	s_nop 1
	v_add_f32_dpp v56, v56, v56 row_ror:2 row_mask:0xf bank_mask:0xf bound_ctrl:1
	s_nop 1
	v_add_f32_dpp v56, v56, v56 row_ror:1 row_mask:0xf bank_mask:0xf bound_ctrl:1
	v_mov_b32_e32 v57, v56
	s_nop 1
	v_permlane16_swap_b32_e32 v56, v57
	v_add_f32_e32 v56, v56, v57
	v_mov_b32_e32 v57, v56
	s_nop 1
	v_permlane32_swap_b32_e32 v56, v57
	v_add_f32_e32 v56, v56, v57
	v_fmamk_f32 v56, v56, 0x3a800000, v70
	v_mul_f32_e32 v57, 0x4f800000, v56
	v_cmp_gt_f32_e32 vcc, s33, v56
	s_nop 1
	v_cndmask_b32_e32 v56, v56, v57, vcc
	v_sqrt_f32_e32 v57, v56
	s_nop 0
	v_add_u32_e32 v58, -1, v57
	v_add_u32_e32 v59, 1, v57
	v_fma_f32 v60, -v58, v57, v56
	v_fma_f32 v61, -v59, v57, v56
	v_cmp_ge_f32_e64 s[2:3], 0, v60
	s_nop 1
	v_cndmask_b32_e64 v57, v57, v58, s[2:3]
	v_cmp_lt_f32_e64 s[2:3], 0, v61
	s_nop 1
	v_cndmask_b32_e64 v57, v57, v59, s[2:3]
	v_mul_f32_e32 v58, 0x37800000, v57
	v_cndmask_b32_e32 v57, v57, v58, vcc
	v_cmp_class_f32_e32 vcc, v56, v71
	s_nop 1
	v_cndmask_b32_e32 v56, v57, v56, vcc
	v_div_scale_f32 v57, s[2:3], v56, v56, 1.0
	v_rcp_f32_e32 v59, v57
	v_div_scale_f32 v58, vcc, 1.0, v56, 1.0
	s_lshl_b64 s[2:3], s[26:27], 11
	v_fma_f32 v60, -v57, v59, 1.0
	v_fmac_f32_e32 v59, v60, v59
	v_mul_f32_e32 v60, v58, v59
	v_fma_f32 v61, -v57, v60, v58
	v_fmac_f32_e32 v60, v61, v59
	v_fma_f32 v57, -v57, v60, v58
	v_div_fmas_f32 v57, v57, v59, v60
	v_div_fixup_f32 v56, v57, v56, 1.0
	v_pk_mul_f32 v[176:177], v[176:177], v[56:57] op_sel_hi:[1,0]
	v_pk_mul_f32 v[178:179], v[178:179], v[56:57] op_sel_hi:[1,0]
	v_pk_fma_f32 v[176:177], v[8:9], v[176:177], v[0:1]
	v_pk_mul_f32 v[180:181], v[180:181], v[56:57] op_sel_hi:[1,0]
	v_pk_mul_f32 v[182:183], v[182:183], v[56:57] op_sel_hi:[1,0]
	v_pk_fma_f32 v[178:179], v[10:11], v[178:179], v[2:3]
	v_cvt_pk_bf16_f32 v176, v176, v177
	v_pk_mul_f32 v[184:185], v[184:185], v[56:57] op_sel_hi:[1,0]
	v_cvt_pk_bf16_f32 v177, v178, v179
	v_pk_mul_f32 v[186:187], v[186:187], v[56:57] op_sel_hi:[1,0]
	v_pk_fma_f32 v[182:183], v[14:15], v[182:183], v[6:7]
	v_pk_fma_f32 v[180:181], v[12:13], v[180:181], v[4:5]
	global_store_dwordx2 v[62:63], v[176:177], off
	v_cvt_pk_bf16_f32 v176, v180, v181
	v_cvt_pk_bf16_f32 v177, v182, v183
	v_pk_mul_f32 v[188:189], v[188:189], v[56:57] op_sel_hi:[1,0]
	v_pk_mul_f32 v[190:191], v[190:191], v[56:57] op_sel_hi:[1,0]
	v_pk_fma_f32 v[186:187], v[26:27], v[186:187], v[18:19]
	v_pk_fma_f32 v[184:185], v[24:25], v[184:185], v[16:17]
	global_store_dwordx2 v[62:63], v[176:177], off offset:512
	v_cvt_pk_bf16_f32 v176, v184, v185
	v_cvt_pk_bf16_f32 v177, v186, v187
	v_pk_fma_f32 v[190:191], v[30:31], v[190:191], v[22:23]
	v_pk_fma_f32 v[188:189], v[28:29], v[188:189], v[20:21]
	global_store_dwordx2 v[62:63], v[176:177], off offset:1024
	v_cvt_pk_bf16_f32 v176, v188, v189
	v_cvt_pk_bf16_f32 v177, v190, v191
	global_store_dwordx2 v[62:63], v[176:177], off offset:1536
	v_lshl_add_u64 v[56:57], v[48:49], 0, s[2:3]
	s_waitcnt vmcnt(59)
	v_cvt_pk_bf16_f32 v60, v192, v193
	v_mul_f32_e32 v62, v193, v193
	v_mul_f32_e32 v63, v195, v195
	s_waitcnt vmcnt(58)
	v_mul_f32_e32 v64, v197, v197
	v_mul_f32_e32 v65, v199, v199
	v_cvt_pk_bf16_f32 v61, v194, v195
	s_waitcnt vmcnt(57)
	v_mul_f32_e32 v72, v201, v201
	v_mul_f32_e32 v73, v203, v203
	v_fmac_f32_e32 v62, v192, v192
	v_fmac_f32_e32 v63, v194, v194
	v_fmac_f32_e32 v64, v196, v196
	v_fmac_f32_e32 v65, v198, v198
	s_waitcnt vmcnt(56)
	v_mul_f32_e32 v74, v205, v205
	v_mul_f32_e32 v75, v207, v207
	global_store_dwordx2 v[56:57], v[60:61], off
	v_cvt_pk_bf16_f32 v60, v196, v197
	v_cvt_pk_bf16_f32 v61, v198, v199
	v_fmac_f32_e32 v72, v200, v200
	v_fmac_f32_e32 v73, v202, v202
	v_add_f32_e32 v62, v62, v63
	v_add_f32_e32 v63, v64, v65
	v_fmac_f32_e32 v74, v204, v204
	v_fmac_f32_e32 v75, v206, v206
	global_store_dwordx2 v[56:57], v[60:61], off offset:512
	v_cvt_pk_bf16_f32 v60, v200, v201
	v_cvt_pk_bf16_f32 v61, v202, v203
	v_add_f32_e32 v64, v72, v73
	v_add_f32_e32 v62, v62, v63
	v_add_f32_e32 v65, v74, v75
	global_store_dwordx2 v[56:57], v[60:61], off offset:1024
	v_cvt_pk_bf16_f32 v60, v204, v205
	v_cvt_pk_bf16_f32 v61, v206, v207
	global_store_dwordx2 v[56:57], v[60:61], off offset:1536
	v_add_f32_e32 v56, v62, v64
	v_add_f32_e32 v56, v56, v65
	v_lshl_add_u64 v[58:59], v[50:51], 0, s[2:3]
	s_add_u32 s20, s20, 4
	v_add_f32_dpp v56, v56, v56 row_ror:8 row_mask:0xf bank_mask:0xf bound_ctrl:1
	s_addc_u32 s21, s21, 0
	s_cmp_eq_u32 s20, 8
	v_add_f32_dpp v56, v56, v56 row_ror:4 row_mask:0xf bank_mask:0xf bound_ctrl:1
	s_nop 1
	v_add_f32_dpp v56, v56, v56 row_ror:2 row_mask:0xf bank_mask:0xf bound_ctrl:1
	s_nop 1
	v_add_f32_dpp v56, v56, v56 row_ror:1 row_mask:0xf bank_mask:0xf bound_ctrl:1
	v_mov_b32_e32 v57, v56
	s_nop 1
	v_permlane16_swap_b32_e32 v56, v57
	v_add_f32_e32 v56, v56, v57
	v_mov_b32_e32 v57, v56
	s_nop 1
	v_permlane32_swap_b32_e32 v56, v57
	v_add_f32_e32 v56, v56, v57
	v_fmamk_f32 v56, v56, 0x3a800000, v70
	v_mul_f32_e32 v57, 0x4f800000, v56
	v_cmp_gt_f32_e32 vcc, s33, v56
	s_nop 1
	v_cndmask_b32_e32 v56, v56, v57, vcc
	v_sqrt_f32_e32 v57, v56
	s_nop 0
	v_add_u32_e32 v60, -1, v57
	v_add_u32_e32 v61, 1, v57
	v_fma_f32 v62, -v60, v57, v56
	v_fma_f32 v63, -v61, v57, v56
	v_cmp_ge_f32_e64 s[2:3], 0, v62
	s_nop 1
	v_cndmask_b32_e64 v57, v57, v60, s[2:3]
	v_cmp_lt_f32_e64 s[2:3], 0, v63
	s_nop 1
	v_cndmask_b32_e64 v57, v57, v61, s[2:3]
	v_mul_f32_e32 v60, 0x37800000, v57
	v_cndmask_b32_e32 v57, v57, v60, vcc
	v_cmp_class_f32_e32 vcc, v56, v71
	s_nop 1
	v_cndmask_b32_e32 v56, v57, v56, vcc
	v_div_scale_f32 v57, s[2:3], v56, v56, 1.0
	v_rcp_f32_e32 v61, v57
	v_div_scale_f32 v60, vcc, 1.0, v56, 1.0
	v_fma_f32 v62, -v57, v61, 1.0
	v_fmac_f32_e32 v61, v62, v61
	v_mul_f32_e32 v62, v60, v61
	v_fma_f32 v63, -v57, v62, v60
	v_fmac_f32_e32 v62, v63, v61
	v_fma_f32 v57, -v57, v62, v60
	v_div_fmas_f32 v57, v57, v61, v62
	v_div_fixup_f32 v56, v57, v56, 1.0
	v_pk_mul_f32 v[192:193], v[192:193], v[56:57] op_sel_hi:[1,0]
	v_pk_mul_f32 v[194:195], v[194:195], v[56:57] op_sel_hi:[1,0]
	v_pk_fma_f32 v[192:193], v[8:9], v[192:193], v[0:1]
	v_pk_mul_f32 v[196:197], v[196:197], v[56:57] op_sel_hi:[1,0]
	v_pk_mul_f32 v[198:199], v[198:199], v[56:57] op_sel_hi:[1,0]
	v_pk_fma_f32 v[194:195], v[10:11], v[194:195], v[2:3]
	v_cvt_pk_bf16_f32 v192, v192, v193
	v_pk_mul_f32 v[200:201], v[200:201], v[56:57] op_sel_hi:[1,0]
	v_cvt_pk_bf16_f32 v193, v194, v195
	v_pk_mul_f32 v[202:203], v[202:203], v[56:57] op_sel_hi:[1,0]
	v_pk_fma_f32 v[198:199], v[14:15], v[198:199], v[6:7]
	v_pk_fma_f32 v[196:197], v[12:13], v[196:197], v[4:5]
	global_store_dwordx2 v[58:59], v[192:193], off
	v_cvt_pk_bf16_f32 v192, v196, v197
	v_cvt_pk_bf16_f32 v193, v198, v199
	v_pk_mul_f32 v[204:205], v[204:205], v[56:57] op_sel_hi:[1,0]
	v_pk_mul_f32 v[206:207], v[206:207], v[56:57] op_sel_hi:[1,0]
	v_pk_fma_f32 v[202:203], v[26:27], v[202:203], v[18:19]
	v_pk_fma_f32 v[200:201], v[24:25], v[200:201], v[16:17]
	global_store_dwordx2 v[58:59], v[192:193], off offset:512
	v_cvt_pk_bf16_f32 v192, v200, v201
	v_cvt_pk_bf16_f32 v193, v202, v203
	v_pk_fma_f32 v[206:207], v[30:31], v[206:207], v[22:23]
	v_pk_fma_f32 v[204:205], v[28:29], v[204:205], v[20:21]
	global_store_dwordx2 v[58:59], v[192:193], off offset:1024
	v_cvt_pk_bf16_f32 v192, v204, v205
	v_cvt_pk_bf16_f32 v193, v206, v207
	global_store_dwordx2 v[58:59], v[192:193], off offset:1536
	s_cmp_eq_u32 s20, 8
	s_cbranch_scc0 .LBB0_110
	s_add_u32 s12, s12, s14
	s_addc_u32 s13, s13, s15
	s_cmpk_gt_i32 s12, 0x3fff
	v_lshl_add_u64 v[52:53], v[52:53], 0, s[16:17]
	s_cbranch_scc0 .LBB0_109
